# v34: v33 + the five MLA staging LDS-DMAs spread over the first five QK steps (issue under MFMA execution)
# baseline (speedup 1.0000x reference)
; #define LAS __attribute__((address_space(3)))
; #define SBAR() __builtin_amdgcn_sched_barrier(0)
; #define KRD2(f0, f1, ka_, m_) do { KRD(f0, kbo + ka_, (m_) * 128); KRD(f1, kbo + ka_, (m_) * 128 + 8192); } while (0)
; #define KMMA(f0, f1, q_) do { p0 = __builtin_amdgcn_mfma_f32_32x32x16_bf16(f0, q_, p0, 0, 0, 0); p1 = __builtin_amdgcn_mfma_f32_32x32x16_bf16(f1, q_, p1, 0, 0, 0); } while (0)
; #define KWAIT(n_) do { asm volatile("s_waitcnt lgkmcnt(" #n_ ")" ::: "memory"); SBAR(); } while (0)
; #define PRD3(f0, f1, qf, pa_, d_) do { KRD(f0, pbo + pa_, 0); KRD(f1, pbo + pa_, 4096); KRD(qf, qpo, (d_) * 1024); } while (0)
;     ...
;             const LAS unsigned char* Ks = lds + buf * BUF; const LAS unsigned char* Ps = Ks + SHM_K + SHM_V;
;             f32x16 p0, p1;
; #pragma unroll
;             for (int r = 0; r < 16; ++r) { p0[r] = 0.f; p1[r] = 0.f; }
;             if constexpr (ABL != 3) {
;             const int kbo = (int)(uintptr_t)Ks;
;             bf16x8 fa0, fa1, fb0, fb1;
;     ...
;             KRD2(fa0, fa1, ka0, 0); KRD2(fb0, fb1, ka1, 0);
;             KWAIT(2); KMMA(fa0, fa1, qr[0]); SBAR(); KRD2(fa0, fa1, ka2, 0);
;             KWAIT(2); KMMA(fb0, fb1, qr[1]); SBAR(); KRD2(fb0, fb1, ka3, 0);
;             KWAIT(2); KMMA(fa0, fa1, qr[2]); SBAR(); KRD2(fa0, fa1, ka0, 1);
;             KWAIT(2); KMMA(fb0, fb1, qr[3]); SBAR(); KRD2(fb0, fb1, ka1, 1);
;             KWAIT(2); KMMA(fa0, fa1, qr[4]); SBAR(); KRD2(fa0, fa1, ka2, 1);
;             KWAIT(2); KMMA(fb0, fb1, qr[5]); SBAR(); KRD2(fb0, fb1, ka3, 1);
;             if constexpr (DPE == 64) {
;                 const int pbo = (int)(uintptr_t)Ps; const int qpo = (int)(uintptr_t)qpl; bf16x8 qfa, qfb;
;     ...
;                 KWAIT(2); KMMA(fa0, fa1, qr[6]); SBAR(); PRD3(fa0, fa1, qfa, pa_0, 0);
;                 KWAIT(3); KMMA(fb0, fb1, qr[7]); SBAR(); PRD3(fb0, fb1, qfb, pa_1, 1);
;                 KWAIT(3); KMMA(fa0, fa1, qfa); SBAR(); PRD3(fa0, fa1, qfa, pa_2, 2);
;                 KWAIT(3); KMMA(fb0, fb1, qfb); SBAR(); PRD3(fb0, fb1, qfb, pa_3, 3);
;                 KWAIT(3); KMMA(fa0, fa1, qfa); SBAR();
;                 KWAIT(0); KMMA(fb0, fb1, qfb);
.Latt_qk:
	ds_read_b128 v[4:7], v196 offset:0
	ds_read_b128 v[8:11], v196 offset:8192
	ds_read_b128 v[12:15], v197 offset:0
	ds_read_b128 v[188:191], v197 offset:8192
	ds_read_b128 v[192:195], v198 offset:0
	ds_read_b128 v[214:217], v198 offset:8192
	ds_read_b128 v[218:221], v199 offset:0
	ds_read_b128 v[234:237], v199 offset:8192
	s_and_b64 vcc, exec, s[48:49]
	s_waitcnt lgkmcnt(6)
	v_mfma_f32_32x32x16_bf16 v[82:97], v[4:7], v[114:117], 0
	v_mfma_f32_32x32x16_bf16 v[98:113], v[8:11], v[114:117], 0
	ds_read_b128 v[238:241], v196 offset:128
	ds_read_b128 v[242:245], v196 offset:8320
	s_cbranch_vccnz .Latt_ns0
	s_add_i32 s0, s27, 0xffff6000
	s_cmp_lg_u32 s25, 0
	s_cselect_b32 s0, s0, 0x14000
	s_add_i32 s0, s58, s0
	v_lshl_add_u64 v[16:17], s[34:35], 0, v[158:159]
	s_mov_b32 m0, s0
	s_nop 0
	global_load_lds_dwordx4 v[16:17], off
.Latt_ns0:
	s_waitcnt lgkmcnt(6)
	v_mfma_f32_32x32x16_bf16 v[82:97], v[12:15], v[118:121], v[82:97]
	v_mfma_f32_32x32x16_bf16 v[98:113], v[188:191], v[118:121], v[98:113]
	ds_read_b128 v[246:249], v197 offset:128
	ds_read_b128 v[222:225], v197 offset:8320
	s_cbranch_vccnz .Latt_ns1
	v_lshl_add_u64 v[16:17], s[34:35], 0, v[160:161]
	s_add_i32 m0, s0, 0x2000
	s_nop 0
	global_load_lds_dwordx4 v[16:17], off
.Latt_ns1:
	s_waitcnt lgkmcnt(6)
	v_mfma_f32_32x32x16_bf16 v[82:97], v[192:195], v[122:125], v[82:97]
	v_mfma_f32_32x32x16_bf16 v[98:113], v[214:217], v[122:125], v[98:113]
	ds_read_b128 v[4:7], v198 offset:128
	ds_read_b128 v[8:11], v198 offset:8320
	s_cbranch_vccnz .Latt_ns2
	v_lshl_add_u64 v[16:17], s[34:35], 0, v[156:157]
	s_add_i32 m0, s0, 0x4000
	s_nop 0
	global_load_lds_dwordx4 v[16:17], off
.Latt_ns2:
	s_waitcnt lgkmcnt(6)
	v_mfma_f32_32x32x16_bf16 v[82:97], v[218:221], v[126:129], v[82:97]
	v_mfma_f32_32x32x16_bf16 v[98:113], v[234:237], v[126:129], v[98:113]
	ds_read_b128 v[12:15], v199 offset:128
	ds_read_b128 v[188:191], v199 offset:8320
	s_cbranch_vccnz .Latt_ns3
	v_lshl_add_u64 v[16:17], s[34:35], 0, v[154:155]
	s_add_i32 m0, s0, 0x6000
	s_nop 0
	global_load_lds_dwordx4 v[16:17], off
.Latt_ns3:
	s_waitcnt lgkmcnt(6)
	v_mfma_f32_32x32x16_bf16 v[82:97], v[238:241], v[130:133], v[82:97]
	v_mfma_f32_32x32x16_bf16 v[98:113], v[242:245], v[130:133], v[98:113]
	ds_read_b128 v[192:195], v162
	ds_read_b128 v[214:217], v162 offset:4096
	ds_read_b128 v[210:213], v183 offset:0
	s_cbranch_vccnz .Latt_ns4
	v_lshl_add_u64 v[16:17], s[34:35], 0, v[152:153]
	s_add_i32 m0, s0, 0x8000
	s_nop 0
	global_load_lds_dwordx4 v[16:17], off
.Latt_ns4:
	s_waitcnt lgkmcnt(7)
	v_mfma_f32_32x32x16_bf16 v[82:97], v[246:249], v[134:137], v[82:97]
	v_mfma_f32_32x32x16_bf16 v[98:113], v[222:225], v[134:137], v[98:113]
	ds_read_b128 v[218:221], v163
	ds_read_b128 v[234:237], v163 offset:4096
	ds_read_b128 v[202:205], v183 offset:1024
	s_waitcnt lgkmcnt(8)
	v_mfma_f32_32x32x16_bf16 v[82:97], v[4:7], v[138:141], v[82:97]
	v_mfma_f32_32x32x16_bf16 v[98:113], v[8:11], v[138:141], v[98:113]
	ds_read_b128 v[238:241], v164
	ds_read_b128 v[242:245], v164 offset:4096
	ds_read_b128 v[230:233], v183 offset:2048
	s_waitcnt lgkmcnt(9)
	v_mfma_f32_32x32x16_bf16 v[82:97], v[12:15], v[142:145], v[82:97]
	v_mfma_f32_32x32x16_bf16 v[98:113], v[188:191], v[142:145], v[98:113]
	ds_read_b128 v[246:249], v165
	ds_read_b128 v[222:225], v165 offset:4096
	ds_read_b128 v[206:209], v183 offset:3072
	s_waitcnt lgkmcnt(9)
	v_mfma_f32_32x32x16_bf16 v[82:97], v[192:195], v[210:213], v[82:97]
	v_mfma_f32_32x32x16_bf16 v[98:113], v[214:217], v[210:213], v[98:113]
	s_waitcnt lgkmcnt(6)
	v_mfma_f32_32x32x16_bf16 v[82:97], v[218:221], v[202:205], v[82:97]
	v_mfma_f32_32x32x16_bf16 v[98:113], v[234:237], v[202:205], v[98:113]
	s_waitcnt lgkmcnt(3)
	v_mfma_f32_32x32x16_bf16 v[82:97], v[238:241], v[230:233], v[82:97]
	v_mfma_f32_32x32x16_bf16 v[98:113], v[242:245], v[230:233], v[98:113]
	s_waitcnt lgkmcnt(0)
; DI int crow(int r, int hi) { return (r & 3) + 8 * (r >> 2) + 4 * hi; }
;     ...
;             float alpha = 1.f;
;             if constexpr (ABL != 1) {
;             float pmax = p0[0];
; #pragma unroll
;             for (int r = 1; r < 16; ++r) pmax = fmaxf(pmax, p0[r]);
; #pragma unroll
;             for (int r = 0; r < 16; ++r) pmax = fmaxf(pmax, p1[r]);
;             { auto rr = __builtin_amdgcn_permlane32_swap(__float_as_uint(pmax), __float_as_uint(pmax), false, false); pmax = fmaxf(__uint_as_float(rr[0]), __uint_as_float(rr[1])); }
;             float mn;
;             if (__all(pmax - m_reg <= thr_raw)) { mn = m_reg; alpha = 1.f; }
;             else { mn = fmaxf(m_reg, pmax); alpha = __builtin_amdgcn_exp2f((m_reg - mn) * C); m_reg = mn; }
;             const float mnC = -mn * C;
; #pragma unroll
;             for (int r = 0; r < 16; ++r) { p0[r] = __builtin_amdgcn_exp2f(fmaf(p0[r], C, mnC)); p1[r] = __builtin_amdgcn_exp2f(fmaf(p1[r], C, mnC)); }
;             float ps = 0.f;
; #pragma unroll
;             for (int r = 0; r < 16; ++r) ps += p0[r] + p1[r];
;             { auto rr = __builtin_amdgcn_permlane32_swap(__float_as_uint(ps), __float_as_uint(ps), false, false); ps = __uint_as_float(rr[0]) + __uint_as_float(rr[1]); }
;             l_reg = l_reg * alpha + ps;
;             }
;             bf16x8 pa0, pa1, pa2, pa3;
;     ...
;             PK4(p0, 0, pa0); PK4(p0, 8, pa1); PK4(p1, 0, pa2); PK4(p1, 8, pa3);
;     ...
;             if (__any(alpha < 1.f)) { if (hi == 0) al_l[r32] = alpha; asm volatile("s_waitcnt lgkmcnt(0)" ::: "memory");
; #pragma unroll
;                 for (int r = 0; r < 16; ++r) { const float a = al_l[crow(r, hi)];
; #pragma unroll
;                     for (int d = 0; d < 4; ++d) o[d][r] *= a; } }
	v_mfma_f32_32x32x16_bf16 v[82:97], v[246:249], v[206:209], v[82:97]
	v_mfma_f32_32x32x16_bf16 v[98:113], v[222:225], v[206:209], v[98:113]
	s_mov_b32 s0, 0x42ddb3d8
	s_nop 10
	v_max_f32_e32 v2, v83, v83
	v_max_f32_e32 v4, v82, v82
	v_max_f32_e32 v2, v4, v2
	v_max3_f32 v2, v2, v84, v85
	v_max3_f32 v2, v2, v86, v87
	v_max3_f32 v2, v2, v88, v89
	v_max3_f32 v2, v2, v90, v91
	v_max3_f32 v2, v2, v92, v93
	v_max3_f32 v2, v2, v94, v95
	v_max3_f32 v2, v2, v96, v97
	v_max_f32_e32 v4, v185, v185
	v_max3_f32 v2, v2, v98, v99
	v_max3_f32 v2, v2, v100, v101
	v_max3_f32 v2, v2, v102, v103
	v_max3_f32 v2, v2, v104, v105
	v_max3_f32 v2, v2, v106, v107
	v_max3_f32 v2, v2, v108, v109
	v_max3_f32 v2, v2, v110, v111
	v_max3_f32 v2, v2, v112, v113
	v_mov_b32_e32 v5, v2
	s_nop 1
	v_permlane32_swap_b32_e32 v2, v5
	v_max_f32_e32 v5, v5, v5
	v_max_f32_e32 v2, v2, v2
	v_max_f32_e32 v2, v2, v5
	v_sub_f32_e32 v5, v2, v185
	v_cmp_ge_f32_e32 vcc, s0, v5
	s_cmp_eq_u64 vcc, exec
	v_max_f32_e32 v2, v4, v2
	s_cselect_b64 vcc, -1, 0
	v_sub_f32_e32 v4, v185, v2
	v_cndmask_b32_e32 v185, v2, v185, vcc
	v_mul_f32_e32 v2, 0xbdd53b94, v185
	v_fmamk_f32 v5, v82, 0x3dd53b94, v2
	v_fmamk_f32 v6, v98, 0x3dd53b94, v2
	v_fmamk_f32 v7, v83, 0x3dd53b94, v2
	v_fmamk_f32 v8, v99, 0x3dd53b94, v2
	v_fmamk_f32 v10, v100, 0x3dd53b94, v2
	v_exp_f32_e32 v5, v5
	v_exp_f32_e32 v100, v6
	v_fmamk_f32 v9, v84, 0x3dd53b94, v2
	v_fmamk_f32 v12, v101, 0x3dd53b94, v2
	v_exp_f32_e32 v6, v7
	v_exp_f32_e32 v101, v8
	v_fmamk_f32 v11, v85, 0x3dd53b94, v2
	v_fmamk_f32 v14, v102, 0x3dd53b94, v2
	v_exp_f32_e32 v7, v9
	v_exp_f32_e32 v102, v10
	v_fmamk_f32 v13, v86, 0x3dd53b94, v2
	v_fmamk_f32 v15, v87, 0x3dd53b94, v2
	v_fmamk_f32 v16, v103, 0x3dd53b94, v2
	v_fmamk_f32 v17, v88, 0x3dd53b94, v2
	v_fmamk_f32 v82, v104, 0x3dd53b94, v2
	v_fmamk_f32 v83, v89, 0x3dd53b94, v2
	v_fmamk_f32 v84, v105, 0x3dd53b94, v2
	v_fmamk_f32 v85, v90, 0x3dd53b94, v2
	v_fmamk_f32 v86, v106, 0x3dd53b94, v2
	v_fmamk_f32 v87, v91, 0x3dd53b94, v2
	v_fmamk_f32 v88, v107, 0x3dd53b94, v2
	v_fmamk_f32 v89, v92, 0x3dd53b94, v2
	v_fmamk_f32 v90, v108, 0x3dd53b94, v2
	v_fmamk_f32 v91, v93, 0x3dd53b94, v2
	v_fmamk_f32 v92, v109, 0x3dd53b94, v2
	v_fmamk_f32 v93, v94, 0x3dd53b94, v2
	v_fmamk_f32 v94, v110, 0x3dd53b94, v2
	v_fmamk_f32 v95, v95, 0x3dd53b94, v2
	v_fmamk_f32 v98, v111, 0x3dd53b94, v2
	v_fmamk_f32 v96, v96, 0x3dd53b94, v2
	v_fmamk_f32 v99, v112, 0x3dd53b94, v2
	v_fmamk_f32 v97, v97, 0x3dd53b94, v2
	v_fmac_f32_e32 v2, 0x3dd53b94, v113
	v_exp_f32_e32 v8, v11
	v_exp_f32_e32 v103, v12
	v_exp_f32_e32 v9, v13
	v_exp_f32_e32 v14, v14
	v_exp_f32_e32 v12, v83
	v_exp_f32_e32 v83, v84
	v_exp_f32_e32 v84, v86
	v_exp_f32_e32 v86, v88
	v_exp_f32_e32 v88, v90
	v_exp_f32_e32 v90, v92
	v_exp_f32_e32 v92, v94
	v_exp_f32_e32 v94, v98
	v_exp_f32_e32 v98, v2
	v_add_f32_e32 v2, v5, v100
	v_exp_f32_e32 v10, v15
	v_exp_f32_e32 v15, v16
	v_add_f32_e32 v16, v6, v101
	v_add_f32_e32 v2, 0, v2
	v_exp_f32_e32 v11, v17
	v_exp_f32_e32 v82, v82
	v_add_f32_e32 v17, v7, v102
	v_add_f32_e32 v2, v16, v2
	v_exp_f32_e32 v13, v85
	v_exp_f32_e32 v85, v87
	v_exp_f32_e32 v87, v89
	v_exp_f32_e32 v89, v91
	v_exp_f32_e32 v91, v93
	v_exp_f32_e32 v93, v95
	v_exp_f32_e32 v95, v96
	v_exp_f32_e32 v96, v99
	v_add_f32_e32 v99, v8, v103
	v_add_f32_e32 v2, v17, v2
	v_add_f32_e32 v104, v9, v14
	v_add_f32_e32 v2, v99, v2
	v_add_f32_e32 v105, v10, v15
	v_add_f32_e32 v2, v104, v2
	v_add_f32_e32 v106, v11, v82
	v_add_f32_e32 v2, v105, v2
	v_add_f32_e32 v2, v106, v2
	v_add_f32_e32 v16, v12, v83
	v_add_f32_e32 v2, v16, v2
	v_add_f32_e32 v16, v13, v84
	v_add_f32_e32 v2, v16, v2
	v_add_f32_e32 v16, v85, v86
	v_add_f32_e32 v2, v16, v2
	v_add_f32_e32 v16, v87, v88
	v_exp_f32_e32 v97, v97
	v_add_f32_e32 v2, v16, v2
	v_add_f32_e32 v16, v89, v90
	v_mul_f32_e32 v4, 0x3dd53b94, v4
	v_add_f32_e32 v2, v16, v2
	v_add_f32_e32 v16, v91, v92
	v_exp_f32_e32 v4, v4
	v_add_f32_e32 v2, v16, v2
	v_add_f32_e32 v16, v93, v94
	v_add_f32_e32 v2, v16, v2
	v_add_f32_e32 v16, v95, v96
	v_add_f32_e32 v2, v16, v2
	v_add_f32_e32 v16, v97, v98
	v_add_f32_e32 v16, v16, v2
	v_cndmask_b32_e64 v2, v4, 1.0, vcc
	v_mov_b32_e32 v17, v16
	v_cvt_pk_bf16_f32 v4, v5, v6
	v_cvt_pk_bf16_f32 v5, v7, v8
	v_cvt_pk_bf16_f32 v6, v9, v10
	v_cvt_pk_bf16_f32 v7, v11, v12
	v_cvt_pk_bf16_f32 v8, v13, v85
	v_cvt_pk_bf16_f32 v9, v87, v89
	v_cvt_pk_bf16_f32 v10, v91, v93
	v_cvt_pk_bf16_f32 v11, v95, v97
	v_cvt_pk_bf16_f32 v12, v100, v101
	v_cvt_pk_bf16_f32 v13, v102, v103
	v_cvt_pk_bf16_f32 v14, v14, v15
	v_cvt_pk_bf16_f32 v15, v82, v83
	v_cvt_pk_bf16_f32 v82, v84, v86
	v_cvt_pk_bf16_f32 v83, v88, v90
	v_cvt_pk_bf16_f32 v84, v92, v94
	v_cvt_pk_bf16_f32 v85, v96, v98
	v_permlane32_swap_b32_e32 v16, v17
	v_permlane32_swap_b32_e32 v4, v6
	v_permlane32_swap_b32_e32 v5, v7
	v_permlane32_swap_b32_e32 v8, v10
	v_permlane32_swap_b32_e32 v9, v11
	v_permlane32_swap_b32_e32 v12, v14
	v_permlane32_swap_b32_e32 v13, v15
	v_permlane32_swap_b32_e32 v82, v84
	v_permlane32_swap_b32_e32 v83, v85
	v_cmp_gt_f32_e32 vcc, 1.0, v2
	s_cbranch_vccz .LBB0_1192
	s_and_saveexec_b64 s[0:1], s[38:39]
	ds_write_b32 v184, v2 offset:128
	s_or_b64 exec, exec, s[0:1]
	s_waitcnt lgkmcnt(0)
	v_add_u32_e32 v98, s55, v171
	ds_read_b128 v[86:89], v98 offset:224
	ds_read_b128 v[90:93], v98 offset:192
	ds_read_b128 v[94:97], v98 offset:160
	ds_read_b128 v[98:101], v98 offset:128
	s_waitcnt lgkmcnt(0)
	v_pk_mul_f32 v[78:79], v[78:79], v[86:87]
	v_pk_mul_f32 v[74:75], v[74:75], v[90:91]
	v_pk_mul_f32 v[70:71], v[70:71], v[94:95]
	v_pk_mul_f32 v[80:81], v[80:81], v[88:89]
	v_pk_mul_f32 v[76:77], v[76:77], v[92:93]
	v_pk_mul_f32 v[72:73], v[72:73], v[96:97]
	v_pk_mul_f32 v[68:69], v[68:69], v[100:101]
	v_pk_mul_f32 v[66:67], v[66:67], v[98:99]
	v_pk_mul_f32 v[62:63], v[62:63], v[86:87]
	v_pk_mul_f32 v[58:59], v[58:59], v[90:91]
	v_pk_mul_f32 v[54:55], v[54:55], v[94:95]
	v_pk_mul_f32 v[64:65], v[64:65], v[88:89]
	v_pk_mul_f32 v[60:61], v[60:61], v[92:93]
	v_pk_mul_f32 v[56:57], v[56:57], v[96:97]
	v_pk_mul_f32 v[52:53], v[52:53], v[100:101]
	v_pk_mul_f32 v[50:51], v[50:51], v[98:99]
	v_pk_mul_f32 v[46:47], v[46:47], v[86:87]
	v_pk_mul_f32 v[42:43], v[42:43], v[90:91]
	v_pk_mul_f32 v[38:39], v[38:39], v[94:95]
	v_pk_mul_f32 v[48:49], v[48:49], v[88:89]
	v_pk_mul_f32 v[44:45], v[44:45], v[92:93]
	v_pk_mul_f32 v[40:41], v[40:41], v[96:97]
	v_pk_mul_f32 v[36:37], v[36:37], v[100:101]
	v_pk_mul_f32 v[34:35], v[34:35], v[98:99]
	v_pk_mul_f32 v[30:31], v[30:31], v[86:87]
	v_pk_mul_f32 v[26:27], v[26:27], v[90:91]
	v_pk_mul_f32 v[22:23], v[22:23], v[94:95]
	v_pk_mul_f32 v[32:33], v[32:33], v[88:89]
	v_pk_mul_f32 v[28:29], v[28:29], v[92:93]
	v_pk_mul_f32 v[24:25], v[24:25], v[96:97]
	v_pk_mul_f32 v[20:21], v[20:21], v[100:101]
	v_pk_mul_f32 v[18:19], v[18:19], v[98:99]
